# baseline (speedup 1.0000x reference)
.LBB0_110:
	s_or_saveexec_b64 s[88:89], s[28:29]
	v_mov_b32_e32 v224, 2
	s_xor_b64 exec, exec, s[88:89]
	s_cbranch_execz .LBB0_212
	v_cmp_lt_i32_e32 vcc, 3, v223
	s_mov_b64 s[90:91], s[46:47]
	s_and_saveexec_b64 s[8:9], vcc
	s_xor_b64 s[28:29], exec, s[8:9]
	s_or_b64 s[90:91], s[46:47], exec
	s_andn2_saveexec_b64 s[92:93], s[28:29]
	s_cbranch_execz .LBB0_211
	v_mov_b32_e32 v2, v190
	v_cndmask_b32_e64 v3, 0, 64, s[4:5]
	v_and_b32_e32 v0, 63, v2
	v_or_b32_e32 v3, v0, v3
	v_readlane_b32 s36, v255, 44
	v_readlane_b32 s28, v255, 36
	v_lshlrev_b32_e32 v3, 2, v3
	v_readlane_b32 s40, v255, 48
	v_readlane_b32 s41, v255, 49
	v_readlane_b32 s29, v255, 37
	v_readlane_b32 s42, v255, 50
	v_readlane_b32 s43, v255, 51
	s_nop 1
	global_load_dword v4, v3, s[40:41]
	s_nop 1
	global_load_dword v5, v3, s[42:43]
	v_readlane_b32 s30, v255, 38
	v_readlane_b32 s31, v255, 39
	global_load_dword v6, v3, s[28:29]
	s_nop 3
	global_load_dword v3, v3, s[30:31]
	v_lshlrev_b32_e32 v0, 2, v0
	v_xor_b32_e32 v7, 0x80, v0
	v_readlane_b32 s8, v255, 7
	v_readlane_b32 s37, v255, 45
	v_readlane_b32 s38, v255, 46
	v_readlane_b32 s39, v255, 47
	v_readlane_b32 s9, v255, 8
	s_mov_b32 s39, 0x160000
	s_mov_b32 s38, 0x120000
	s_mov_b32 s37, 0x60000
	s_mov_b32 s36, 0x140000
	s_andn2_b64 vcc, exec, s[8:9]
	s_waitcnt vmcnt(2)
	v_mul_f32_e32 v8, v4, v5
	ds_bpermute_b32 v8, v7, v8
	s_waitcnt vmcnt(0)
	v_mul_f32_e32 v9, v6, v3
	ds_bpermute_b32 v7, v7, v9
	v_xor_b32_e32 v9, 64, v0
	s_waitcnt lgkmcnt(1)
	v_fmac_f32_e32 v8, v4, v5
	v_xor_b32_e32 v5, 32, v0
	s_waitcnt lgkmcnt(0)
	v_fmac_f32_e32 v7, v6, v3
	ds_bpermute_b32 v3, v9, v8
	ds_bpermute_b32 v4, v9, v7
	s_waitcnt lgkmcnt(1)
	v_add_f32_e32 v3, v8, v3
	s_waitcnt lgkmcnt(0)
	v_add_f32_e32 v4, v7, v4
	ds_bpermute_b32 v6, v5, v3
	ds_bpermute_b32 v5, v5, v4
	v_xor_b32_e32 v7, 16, v0
	s_waitcnt lgkmcnt(1)
	v_add_f32_e32 v3, v3, v6
	s_waitcnt lgkmcnt(0)
	v_add_f32_e32 v4, v4, v5
	ds_bpermute_b32 v5, v7, v3
	ds_bpermute_b32 v6, v7, v4
	v_xor_b32_e32 v7, 8, v0
	s_waitcnt lgkmcnt(1)
	v_add_f32_e32 v3, v3, v5
	s_waitcnt lgkmcnt(0)
	v_add_f32_e32 v5, v4, v6
	ds_bpermute_b32 v4, v7, v3
	ds_bpermute_b32 v6, v7, v5
	v_xor_b32_e32 v7, 4, v0
	s_waitcnt lgkmcnt(1)
	v_add_f32_e32 v4, v3, v4
	s_waitcnt lgkmcnt(0)
	v_add_f32_e32 v0, v5, v6
	ds_bpermute_b32 v5, v7, v4
	ds_bpermute_b32 v3, v7, v0
	s_cbranch_vccnz .LBB0_211
	s_waitcnt lgkmcnt(1)
	v_add_f32_e32 v4, v4, v5
	v_mul_f32_e32 v5, 0x3fb8aa3b, v4
	s_mov_b32 s2, 0x3fb8aa3b
	v_fma_f32 v6, v4, s2, -v5
	v_rndne_f32_e32 v7, v5
	v_fmac_f32_e32 v6, 0x32a5705f, v4
	v_sub_f32_e32 v5, v5, v7
	v_add_f32_e32 v5, v5, v6
	v_exp_f32_e32 v5, v5
	v_cvt_i32_f32_e32 v6, v7
	s_waitcnt lgkmcnt(0)
	v_add_f32_e32 v0, v0, v3
	v_mov_b32_e32 v3, 0x3e4ccccd
	v_mov_b32_e32 v7, 0x3eb60549
	v_ldexp_f32 v5, v5, v6
	v_mul_f32_e32 v6, 0x3fb8aa3b, v0
	v_cndmask_b32_e64 v3, v3, v7, s[4:5]
	v_fma_f32 v7, v0, s2, -v6
	v_rndne_f32_e32 v8, v6
	v_fmac_f32_e32 v7, 0x32a5705f, v0
	v_sub_f32_e32 v6, v6, v8
	v_add_f32_e32 v6, v6, v7
	v_exp_f32_e32 v6, v6
	v_cvt_i32_f32_e32 v7, v8
	s_mov_b32 s2, 0xc2ce8ed0
	v_cmp_ngt_f32_e32 vcc, s2, v4
	s_mov_b32 s8, 0x42b17218
	v_cndmask_b32_e64 v142, 0, v208, s[4:5]
	v_cndmask_b32_e32 v5, 0, v5, vcc
	v_cmp_nlt_f32_e32 vcc, s8, v4
	v_mov_b32_e32 v143, v1
	v_sub_f32_e32 v161, 1.0, v3
	v_cndmask_b32_e32 v4, v206, v5, vcc
	v_ldexp_f32 v5, v6, v7
	v_cmp_ngt_f32_e32 vcc, s2, v0
	v_readlane_b32 s95, v255, 0
	s_mov_b32 s50, 0x3fb8aa3b
	v_cndmask_b32_e32 v5, 0, v5, vcc
	v_cmp_nlt_f32_e32 vcc, s8, v0
	v_readlane_b32 s8, v255, 1
	v_readlane_b32 s9, v255, 2
	s_load_dwordx2 s[8:9], s[8:9], 0x98
	v_cndmask_b32_e32 v0, v206, v5, vcc
	v_sub_f32_e32 v0, v4, v0
	v_add_f32_e32 v153, v3, v0
	v_cndmask_b32_e64 v0, 0, v207, s[4:5]
	s_waitcnt lgkmcnt(0)
	v_lshl_add_u64 v[140:141], s[8:9], 0, v[0:1]
	v_ashrrev_i32_e32 v0, 2, v2
	v_lshl_add_u64 v[2:3], s[22:23], 0, v[142:143]
	s_mov_b64 s[8:9], 0x2f550000
	v_and_b32_e32 v174, -16, v0
	v_cndmask_b32_e64 v0, 0, v209, s[4:5]
	v_lshl_add_u64 v[144:145], v[2:3], 0, s[8:9]
	s_mov_b64 s[8:9], 0x30e50000
	v_lshl_add_u64 v[146:147], v[2:3], 0, s[8:9]
	v_lshl_add_u64 v[2:3], s[22:23], 0, v[0:1]
	s_mov_b64 s[8:9], 0x2f050000
	v_lshl_add_u64 v[148:149], v[2:3], 0, s[8:9]
	s_mov_b64 s[8:9], 0x30950000
	v_cndmask_b32_e64 v175, 0, 8, s[4:5]
	v_lshl_add_u64 v[150:151], v[2:3], 0, s[8:9]
	v_sub_u32_e32 v176, 0, v174
	v_add_u32_e32 v177, 0x2cd, v174
	v_readfirstlane_b32 s8, v190
	s_nop 3
	s_lshr_b32 s8, s8, 8
	s_cmp_eq_u32 s8, 0
	s_cbranch_scc0 .Lattn_prio_done
	s_setprio 1
